# PREP weight transposes: the four tile loads issued together
# speedup vs baseline: 1.4473x; 1.0051x over previous
; DI int otid() { int t = threadIdx.x; asm volatile("" : "+v"(t)); return t; }
; DI uint4 pack8(const float* f) { uint4 v; v.x = pack2(f[0], f[1]); v.y = pack2(f[2], f[3]); v.z = pack2(f[4], f[5]); v.w = pack2(f[6], f[7]); return v; }
; DI void transpose_tile(const float* __restrict__ src, u16* __restrict__ dst, int K, int N, int tk, int tn, int drow, float* tile) {
;   const int tid = otid();
;   __syncthreads();
; #pragma unroll
;   for (int i = 0; i < 4; ++i) {
;     int kr = (tid >> 4) + 16 * i, nc = (tid & 15) * 4;
;     float4 v = *(const float4*)(src + (size_t)(tk * 64 + kr) * N + tn * 64 + nc);
;     tile[kr * 65 + nc] = v.x; tile[kr * 65 + nc + 1] = v.y; tile[kr * 65 + nc + 2] = v.z; tile[kr * 65 + nc + 3] = v.w;
;   }
;   __syncthreads();
; #pragma unroll
;   for (int i = 0; i < 2; ++i) {
;     int n = (tid >> 3) + 32 * i, kc = (tid & 7) * 8;
;     float f[8];
; #pragma unroll
;     for (int e = 0; e < 8; ++e) f[e] = tile[(kc + e) * 65 + n];
;     *(uint4*)(dst + (size_t)(drow + n) * K + tk * 64 + kc) = pack8(f);
;   }
; }
.LBB0_593:
	s_ashr_i32 s19, s13, 31
	s_mul_i32 s10, s15, s16
	s_mul_i32 s11, s10, s19
	s_mul_hi_u32 s20, s10, s13
	s_add_i32 s11, s20, s11
	s_mul_i32 s10, s10, s13
	s_lshl_b64 s[10:11], s[10:11], 2
	s_add_u32 s10, s0, s10
	s_addc_u32 s11, s1, s11
	s_mul_hi_u32 s0, s6, s13
	s_mul_i32 s1, s6, s19
	s_add_i32 s0, s0, s1
	s_mul_i32 s1, s7, s13
	s_add_i32 s1, s0, s1
	s_mul_i32 s0, s6, s13
	s_lshl_b64 s[0:1], s[0:1], 1
	s_add_u32 s8, s8, s0
	s_addc_u32 s9, s9, s1
	s_ashr_i32 s13, s12, 31
	v_mov_b32_e32 v1, v197
	s_lshl_b32 s0, s18, 6
	s_lshl_b64 s[6:7], s[12:13], 2
	s_add_u32 s6, s10, s6
	v_ashrrev_i32_e32 v8, 4, v1
	v_lshlrev_b32_e32 v2, 4, v1
	s_addc_u32 s7, s11, s7
	v_and_b32_e32 v198, 0xf0, v2
	v_add_u32_e32 v10, s0, v8
	v_lshl_add_u64 v[6:7], s[6:7], 0, v[198:199]
	v_mad_u64_u32 v[2:3], s[6:7], v10, s16, 0
	v_ashrrev_i32_e32 v5, 31, v10
	v_mov_b32_e32 v4, v3
	v_mad_u64_u32 v[4:5], s[6:7], v5, s16, v[4:5]
	v_mov_b32_e32 v3, v4
	v_lshl_add_u64 v[2:3], v[2:3], 2, v[6:7]
	s_waitcnt lgkmcnt(0)
	s_barrier
	global_load_dwordx4 v[2:5], v[2:3], off
	v_add_u32_e32 v32, 16, v10
	v_ashrrev_i32_e32 v35, 31, v32
	v_mad_u64_u32 v[32:33], s[6:7], v32, s16, 0
	v_mov_b32_e32 v34, v33
	v_mad_u64_u32 v[34:35], s[6:7], v35, s16, v[34:35]
	v_mov_b32_e32 v33, v34
	v_lshl_add_u64 v[32:33], v[32:33], 2, v[6:7]
	global_load_dwordx4 v[48:51], v[32:33], off
	v_add_u32_e32 v36, 32, v10
	v_ashrrev_i32_e32 v39, 31, v36
	v_mad_u64_u32 v[36:37], s[6:7], v36, s16, 0
	v_mov_b32_e32 v38, v37
	v_mad_u64_u32 v[38:39], s[6:7], v39, s16, v[38:39]
	v_mov_b32_e32 v37, v38
	v_lshl_add_u64 v[36:37], v[36:37], 2, v[6:7]
	global_load_dwordx4 v[68:71], v[36:37], off
	v_add_u32_e32 v44, 48, v10
	v_ashrrev_i32_e32 v47, 31, v44
	v_mad_u64_u32 v[44:45], s[6:7], v44, s16, 0
	v_mov_b32_e32 v46, v45
	v_mad_u64_u32 v[46:47], s[6:7], v47, s16, v[46:47]
	v_mov_b32_e32 v45, v46
	v_lshl_add_u64 v[44:45], v[44:45], 2, v[6:7]
	global_load_dwordx4 v[72:75], v[44:45], off
	s_movk_i32 s1, 0x104
	v_mad_u64_u32 v[8:9], s[6:7], v8, s1, v[198:199]
	v_add_u32_e32 v9, 0x1040, v8
	v_ashrrev_i32_e32 v24, 3, v1
	v_lshlrev_b32_e32 v1, 3, v1
	v_and_b32_e32 v1, 56, v1
	s_ashr_i32 s1, s0, 31
	v_lshlrev_b32_e32 v198, 1, v1
	v_mul_u32_u24_e32 v1, 0x104, v1
	s_lshl_b64 s[0:1], s[0:1], 1
	v_lshl_add_u32 v1, v24, 2, v1
	s_add_u32 s0, s8, s0
	s_addc_u32 s1, s9, s1
	s_add_i32 s14, s14, s37
	s_cmpk_gt_i32 s14, 0x23cf
	s_waitcnt vmcnt(3)
	ds_write2_b32 v8, v2, v3 offset1:1
	ds_write2_b32 v8, v4, v5 offset0:2 offset1:3
	s_waitcnt vmcnt(2)
	ds_write2_b32 v9, v48, v49 offset1:1
	v_add_u32_e32 v2, 0x1048, v8
	ds_write2_b32 v2, v50, v51 offset1:1
	v_add_u32_e32 v9, 0x2080, v8
	s_waitcnt vmcnt(1)
	ds_write2_b32 v9, v68, v69 offset1:1
	v_add_u32_e32 v2, 0x2088, v8
	ds_write2_b32 v2, v70, v71 offset1:1
	v_add_u32_e32 v6, 0x30c0, v8
	s_waitcnt vmcnt(0)
	ds_write2_b32 v6, v72, v73 offset1:1
	v_add_u32_e32 v2, 0x30c8, v8
	ds_write2_b32 v2, v74, v75 offset1:1
	s_waitcnt lgkmcnt(0)
	s_barrier
	ds_read2_b32 v[8:9], v1 offset1:32
	ds_read2_b32 v[10:11], v1 offset0:65 offset1:97
	ds_read2_b32 v[12:13], v1 offset0:130 offset1:162
	ds_read2_b32 v[14:15], v1 offset0:195 offset1:227
	v_add_u32_e32 v1, 0x400, v1
	ds_read2_b32 v[16:17], v1 offset0:4 offset1:36
	ds_read2_b32 v[18:19], v1 offset0:69 offset1:101
	ds_read2_b32 v[20:21], v1 offset0:134 offset1:166
	ds_read2_b32 v[22:23], v1 offset0:199 offset1:231
	v_add_u32_e32 v1, s17, v24
	v_lshl_add_u64 v[6:7], s[0:1], 0, v[198:199]
	v_mad_u64_u32 v[24:25], s[0:1], v1, s15, 0
	s_waitcnt lgkmcnt(6)
	v_cvt_pk_bf16_f32 v2, v8, v10
	v_ashrrev_i32_e32 v10, 31, v1
	v_mov_b32_e32 v8, v25
	v_mad_u64_u32 v[26:27], s[0:1], v10, s15, v[8:9]
	v_mov_b32_e32 v25, v26
	s_waitcnt lgkmcnt(4)
	v_cvt_pk_bf16_f32 v3, v12, v14
	s_waitcnt lgkmcnt(2)
	v_cvt_pk_bf16_f32 v4, v16, v18
	s_waitcnt lgkmcnt(0)
	v_cvt_pk_bf16_f32 v5, v20, v22
	v_lshl_add_u64 v[24:25], v[24:25], 1, v[6:7]
	v_add_u32_e32 v1, 32, v1
	global_store_dwordx4 v[24:25], v[2:5], off
	s_nop 1
	v_cvt_pk_bf16_f32 v2, v9, v11
	v_mad_u64_u32 v[8:9], s[0:1], v1, s15, 0
	v_ashrrev_i32_e32 v11, 31, v1
	v_mov_b32_e32 v10, v9
	v_mad_u64_u32 v[10:11], s[0:1], v11, s15, v[10:11]
	v_mov_b32_e32 v9, v10
	v_cvt_pk_bf16_f32 v3, v13, v15
	v_cvt_pk_bf16_f32 v4, v17, v19
	v_cvt_pk_bf16_f32 v5, v21, v23
	v_lshl_add_u64 v[6:7], v[8:9], 1, v[6:7]
	global_store_dwordx4 v[6:7], v[2:5], off
	s_cbranch_scc1 .LBB0_577
